# GEMM K loop: all twelve fragment reads issued behind the barrier, first MFMA group waits for eight (lgkmcnt(4)); no ds_read in the MFMA stream
# speedup vs baseline: 1.0043x; 1.0043x over previous
.LBB0_246:
	s_add_i32 s10, s7, 0xffffa000
	s_cmp_lg_u32 s7, 0
	s_cselect_b32 s12, s10, 0xc000
	v_add_u32_e32 v131, s7, v150
	s_waitcnt vmcnt(6)
	s_barrier
	v_add_u32_e32 v133, s7, v149
	ds_read_b128 v[154:157], v131 offset:0
	ds_read_b128 v[158:161], v131 offset:0x400
	ds_read_b128 v[162:165], v131 offset:0x800
	ds_read_b128 v[166:169], v131 offset:0xc00
	v_add_u32_e32 v131, s12, v147
	ds_read_b128 v[170:173], v133 offset:0
	ds_read_b128 v[174:177], v133 offset:0x400
	ds_read_b128 v[178:181], v133 offset:0x800
	ds_read_b128 v[200:203], v133 offset:0xc00
	ds_read_b128 v[204:207], v133 offset:0x1000
	ds_read_b128 v[208:211], v133 offset:0x1400
	ds_read_b128 v[212:215], v133 offset:0x1800
	ds_read_b128 v[216:219], v133 offset:0x1c00
	s_add_u32 s10, s8, s50
	s_addc_u32 s11, s9, s51
	v_readfirstlane_b32 s13, v131
	s_add_u32 s64, s5, s100
	s_addc_u32 s65, s6, 0
	s_add_i32 s66, s7, 0x6000
	s_cmpk_lg_u32 s7, 0xc000
	s_cselect_b32 s7, s66, 0
	s_addk_i32 s100, 0x400
	s_add_u32 s50, s50, s60
	s_addc_u32 s51, s51, 0
	s_sub_i32 s68, s13, s12
	s_lshr_b32 s68, s68, 1
	s_add_i32 s68, s68, s12
	s_addk_i32 s68, 0x4000
	s_waitcnt lgkmcnt(4)
	v_mfma_f32_16x16x32_bf16 v[126:129], v[154:157], v[170:173], v[126:129]
	v_mfma_f32_16x16x32_bf16 v[122:125], v[154:157], v[174:177], v[122:125]
	v_mfma_f32_16x16x32_bf16 v[118:121], v[154:157], v[178:181], v[118:121]
	v_mfma_f32_16x16x32_bf16 v[114:117], v[154:157], v[200:203], v[114:117]
	s_mov_b32 m0, s13
	v_mfma_f32_16x16x32_bf16 v[110:113], v[158:161], v[170:173], v[110:113]
	global_load_lds_dwordx4 v0, s[10:11]
	v_mfma_f32_16x16x32_bf16 v[102:105], v[158:161], v[174:177], v[102:105]
	v_mfma_f32_16x16x32_bf16 v[94:97], v[158:161], v[178:181], v[94:97]
	s_add_u32 m0, s13, 0x400
	v_mfma_f32_16x16x32_bf16 v[86:89], v[158:161], v[200:203], v[86:89]
	global_load_lds_dwordx4 v130, s[10:11]
	v_mfma_f32_16x16x32_bf16 v[78:81], v[162:165], v[170:173], v[78:81]
	v_mfma_f32_16x16x32_bf16 v[70:73], v[162:165], v[174:177], v[70:73]
	s_add_u32 m0, s13, 0x800
	v_mfma_f32_16x16x32_bf16 v[62:65], v[162:165], v[178:181], v[62:65]
	global_load_lds_dwordx4 v132, s[10:11]
	v_mfma_f32_16x16x32_bf16 v[54:57], v[162:165], v[200:203], v[54:57]
	v_mfma_f32_16x16x32_bf16 v[46:49], v[166:169], v[170:173], v[46:49]
	s_add_u32 m0, s13, 0xc00
	v_mfma_f32_16x16x32_bf16 v[38:41], v[166:169], v[174:177], v[38:41]
	global_load_lds_dwordx4 v136, s[10:11]
	v_mfma_f32_16x16x32_bf16 v[30:33], v[166:169], v[178:181], v[30:33]
	v_mfma_f32_16x16x32_bf16 v[22:25], v[166:169], v[200:203], v[22:25]
	s_waitcnt lgkmcnt(0)
	v_mfma_f32_16x16x32_bf16 v[106:109], v[154:157], v[204:207], v[106:109]
	v_mfma_f32_16x16x32_bf16 v[98:101], v[154:157], v[208:211], v[98:101]
	s_mov_b32 m0, s68
	v_mfma_f32_16x16x32_bf16 v[90:93], v[154:157], v[212:215], v[90:93]
	global_load_lds_dwordx4 v138, s[64:65]
	v_mfma_f32_16x16x32_bf16 v[82:85], v[154:157], v[216:219], v[82:85]
	v_mfma_f32_16x16x32_bf16 v[74:77], v[158:161], v[204:207], v[74:77]
	v_mfma_f32_16x16x32_bf16 v[66:69], v[158:161], v[208:211], v[66:69]
	v_mfma_f32_16x16x32_bf16 v[58:61], v[158:161], v[212:215], v[58:61]
	v_mfma_f32_16x16x32_bf16 v[50:53], v[158:161], v[216:219], v[50:53]
	s_add_u32 m0, s68, 0x400
	v_mfma_f32_16x16x32_bf16 v[42:45], v[162:165], v[204:207], v[42:45]
	global_load_lds_dwordx4 v140, s[64:65]
	v_mfma_f32_16x16x32_bf16 v[34:37], v[162:165], v[208:211], v[34:37]
	v_mfma_f32_16x16x32_bf16 v[26:29], v[162:165], v[212:215], v[26:29]
	v_mfma_f32_16x16x32_bf16 v[18:21], v[162:165], v[216:219], v[18:21]
	v_mfma_f32_16x16x32_bf16 v[14:17], v[166:169], v[204:207], v[14:17]
	v_mfma_f32_16x16x32_bf16 v[10:13], v[166:169], v[208:211], v[10:13]
	v_mfma_f32_16x16x32_bf16 v[6:9], v[166:169], v[212:215], v[6:9]
	v_mfma_f32_16x16x32_bf16 v[2:5], v[166:169], v[216:219], v[2:5]
	s_cmpk_lg_i32 s100, 0x7800
	s_cbranch_scc1 .LBB0_246
	s_waitcnt vmcnt(6)
	s_barrier
	v_add_u32_e32 v0, s7, v150
	v_add_u32_e32 v140, s7, v149
	ds_read_b128 v[130:133], v0 offset:0
	ds_read_b128 v[136:139], v0 offset:0x400
	ds_read_b128 v[154:157], v0 offset:0x800
	ds_read_b128 v[158:161], v0 offset:0xc00
	ds_read_b128 v[162:165], v140 offset:0
	ds_read_b128 v[166:169], v140 offset:0x400
	ds_read_b128 v[170:173], v140 offset:0x800
	ds_read_b128 v[174:177], v140 offset:0xc00
	ds_read_b128 v[178:181], v140 offset:0x1000
	ds_read_b128 v[200:203], v140 offset:0x1400
	ds_read_b128 v[204:207], v140 offset:0x1800
	ds_read_b128 v[208:211], v140 offset:0x1c00
	s_lshl_b32 s49, s4, 8
	s_waitcnt lgkmcnt(4)
	s_nop 0
	v_mfma_f32_16x16x32_bf16 v[126:129], v[130:133], v[162:165], v[126:129]
	v_mfma_f32_16x16x32_bf16 v[118:121], v[130:133], v[170:173], v[118:121]
	v_mfma_f32_16x16x32_bf16 v[114:117], v[130:133], v[174:177], v[114:117]
	v_mfma_f32_16x16x32_bf16 v[110:113], v[136:139], v[162:165], v[110:113]
	v_mfma_f32_16x16x32_bf16 v[102:105], v[136:139], v[166:169], v[102:105]
	v_mfma_f32_16x16x32_bf16 v[94:97], v[136:139], v[170:173], v[94:97]
	v_mfma_f32_16x16x32_bf16 v[86:89], v[136:139], v[174:177], v[86:89]
	v_mfma_f32_16x16x32_bf16 v[70:73], v[154:157], v[166:169], v[70:73]
	v_mfma_f32_16x16x32_bf16 v[62:65], v[154:157], v[170:173], v[62:65]
	v_mfma_f32_16x16x32_bf16 v[54:57], v[154:157], v[174:177], v[54:57]
	v_mfma_f32_16x16x32_bf16 v[46:49], v[158:161], v[162:165], v[46:49]
	v_mfma_f32_16x16x32_bf16 v[38:41], v[158:161], v[166:169], v[38:41]
	v_mfma_f32_16x16x32_bf16 v[30:33], v[158:161], v[170:173], v[30:33]
	v_mfma_f32_16x16x32_bf16 v[22:25], v[158:161], v[174:177], v[22:25]
	v_mfma_f32_16x16x32_bf16 v[212:215], v[130:133], v[166:169], v[122:125]
	v_mfma_f32_16x16x32_bf16 v[216:219], v[154:157], v[162:165], v[78:81]
	s_waitcnt lgkmcnt(0)
	s_nop 0
	v_mfma_f32_16x16x32_bf16 v[174:177], v[136:139], v[178:181], v[74:77]
	v_mfma_f32_16x16x32_bf16 v[220:223], v[136:139], v[200:203], v[66:69]
	v_mfma_f32_16x16x32_bf16 v[224:227], v[136:139], v[204:207], v[58:61]
	v_mfma_f32_16x16x32_bf16 v[50:53], v[136:139], v[208:211], v[50:53]
	v_mfma_f32_16x16x32_bf16 v[136:139], v[154:157], v[178:181], v[42:45]
	v_mfma_f32_16x16x32_bf16 v[34:37], v[154:157], v[200:203], v[34:37]
	v_mfma_f32_16x16x32_bf16 v[6:9], v[158:161], v[204:207], v[6:9]
	v_mfma_f32_16x16x32_bf16 v[162:165], v[130:133], v[178:181], v[106:109]
	v_mfma_f32_16x16x32_bf16 v[166:169], v[130:133], v[200:203], v[98:101]
	v_mfma_f32_16x16x32_bf16 v[170:173], v[130:133], v[204:207], v[90:93]
	v_mfma_f32_16x16x32_bf16 v[130:133], v[130:133], v[208:211], v[82:85]
	v_mfma_f32_16x16x32_bf16 v[228:231], v[154:157], v[204:207], v[26:29]
	v_mfma_f32_16x16x32_bf16 v[154:157], v[154:157], v[208:211], v[18:21]
	v_mfma_f32_16x16x32_bf16 v[178:181], v[158:161], v[178:181], v[14:17]
	v_mfma_f32_16x16x32_bf16 v[200:203], v[158:161], v[200:203], v[10:13]
	v_mfma_f32_16x16x32_bf16 v[158:161], v[158:161], v[208:211], v[2:5]
	s_waitcnt vmcnt(0)
	s_barrier
	ds_read_b128 v[2:5], v151 offset:0
	ds_read_b128 v[14:17], v151 offset:0x400
	ds_read_b128 v[204:207], v151 offset:0x800
	ds_read_b128 v[208:211], v151 offset:0xc00
	ds_read_b128 v[10:13], v152 offset:0
	ds_read_b128 v[18:21], v152 offset:0x400
	ds_read_b128 v[26:29], v152 offset:0x800
	ds_read_b128 v[42:45], v152 offset:0xc00
	ds_read_b128 v[232:235], v152 offset:0x1000
	ds_read_b128 v[236:239], v152 offset:0x1400
	ds_read_b128 v[240:243], v152 offset:0x1800
	ds_read_b128 v[244:247], v152 offset:0x1c00
	s_nop 0
	s_waitcnt lgkmcnt(4)
	s_nop 0
	v_mfma_f32_16x16x32_bf16 v[122:125], v[2:5], v[10:13], v[126:129]
	v_mfma_f32_16x16x32_bf16 v[106:109], v[2:5], v[18:21], v[212:215]
	v_mfma_f32_16x16x32_bf16 v[90:93], v[2:5], v[26:29], v[118:121]
	v_mfma_f32_16x16x32_bf16 v[74:77], v[2:5], v[42:45], v[114:117]
	v_mfma_f32_16x16x32_bf16 v[126:129], v[14:17], v[10:13], v[110:113]
	v_mfma_f32_16x16x32_bf16 v[110:113], v[14:17], v[18:21], v[102:105]
	v_mfma_f32_16x16x32_bf16 v[94:97], v[14:17], v[26:29], v[94:97]
	v_mfma_f32_16x16x32_bf16 v[78:81], v[14:17], v[42:45], v[86:89]
	v_mfma_f32_16x16x32_bf16 v[114:117], v[204:207], v[10:13], v[216:219]
	v_mfma_f32_16x16x32_bf16 v[98:101], v[204:207], v[18:21], v[70:73]
	v_mfma_f32_16x16x32_bf16 v[82:85], v[204:207], v[26:29], v[62:65]
	v_mfma_f32_16x16x32_bf16 v[66:69], v[204:207], v[42:45], v[54:57]
	v_mfma_f32_16x16x32_bf16 v[118:121], v[208:211], v[10:13], v[46:49]
	v_mfma_f32_16x16x32_bf16 v[102:105], v[208:211], v[18:21], v[38:41]
	v_mfma_f32_16x16x32_bf16 v[86:89], v[208:211], v[26:29], v[30:33]
	v_mfma_f32_16x16x32_bf16 v[70:73], v[208:211], v[42:45], v[22:25]
	s_waitcnt lgkmcnt(0)
	s_nop 0
	v_mfma_f32_16x16x32_bf16 v[58:61], v[2:5], v[232:235], v[162:165]
	v_mfma_f32_16x16x32_bf16 v[42:45], v[2:5], v[236:239], v[166:169]
	v_mfma_f32_16x16x32_bf16 v[26:29], v[2:5], v[240:243], v[170:173]
	v_mfma_f32_16x16x32_bf16 v[10:13], v[2:5], v[244:247], v[130:133]
	v_mfma_f32_16x16x32_bf16 v[62:65], v[14:17], v[232:235], v[174:177]
	v_mfma_f32_16x16x32_bf16 v[46:49], v[14:17], v[236:239], v[220:223]
	v_mfma_f32_16x16x32_bf16 v[30:33], v[14:17], v[240:243], v[224:227]
	v_mfma_f32_16x16x32_bf16 v[14:17], v[14:17], v[244:247], v[50:53]
	v_mfma_f32_16x16x32_bf16 v[50:53], v[204:207], v[232:235], v[136:139]
	v_mfma_f32_16x16x32_bf16 v[34:37], v[204:207], v[236:239], v[34:37]
	v_mfma_f32_16x16x32_bf16 v[18:21], v[204:207], v[240:243], v[228:231]
	v_mfma_f32_16x16x32_bf16 v[2:5], v[204:207], v[244:247], v[154:157]
	v_mfma_f32_16x16x32_bf16 v[54:57], v[208:211], v[232:235], v[178:181]
	v_mfma_f32_16x16x32_bf16 v[38:41], v[208:211], v[236:239], v[200:203]
	v_mfma_f32_16x16x32_bf16 v[22:25], v[208:211], v[240:243], v[6:9]
	v_mfma_f32_16x16x32_bf16 v[6:9], v[208:211], v[244:247], v[158:161]
	v_mov_b32_e32 v136, v134
	s_mov_b64 s[50:51], -1
	s_and_b64 vcc, exec, s[22:23]
	s_barrier
	s_cbranch_vccz .LBB0_264
	s_and_b64 vcc, exec, s[0:1]
	s_cbranch_vccz .LBB0_250
	v_lshrrev_b32_e32 v0, 6, v136
	v_mul_lo_u32 v137, v0, s14
	v_and_b32_e32 v130, 15, v136
	v_and_or_b32 v0, v136, 48, v137
	s_movk_i32 s4, 0x90
	v_mad_u32_u24 v0, v130, s4, v0
	v_cvt_pk_bf16_f32 v130, v122, v123
	v_cvt_pk_bf16_f32 v131, v124, v125
	v_cvt_pk_bf16_f32 v132, v126, v127
	v_cvt_pk_bf16_f32 v133, v128, v129
	s_waitcnt vmcnt(0)
	ds_write_b128 v0, v[130:133]
	v_cvt_pk_bf16_f32 v130, v114, v115
	v_cvt_pk_bf16_f32 v131, v116, v117
	v_cvt_pk_bf16_f32 v132, v118, v119
	v_cvt_pk_bf16_f32 v133, v120, v121
	ds_write_b128 v0, v[130:133] offset:64
	v_cvt_pk_bf16_f32 v130, v106, v107
	v_cvt_pk_bf16_f32 v131, v108, v109
	v_cvt_pk_bf16_f32 v132, v110, v111
	v_cvt_pk_bf16_f32 v133, v112, v113
	ds_write_b128 v0, v[130:133] offset:2304
	v_cvt_pk_bf16_f32 v130, v98, v99
	v_cvt_pk_bf16_f32 v131, v100, v101
	v_cvt_pk_bf16_f32 v132, v102, v103
	v_cvt_pk_bf16_f32 v133, v104, v105
	ds_write_b128 v0, v[130:133] offset:2368
	v_cvt_pk_bf16_f32 v130, v90, v91
	v_cvt_pk_bf16_f32 v131, v92, v93
	v_cvt_pk_bf16_f32 v132, v94, v95
	v_cvt_pk_bf16_f32 v133, v96, v97
	ds_write_b128 v0, v[130:133] offset:4608
	v_cvt_pk_bf16_f32 v130, v82, v83
	v_cvt_pk_bf16_f32 v131, v84, v85
	v_cvt_pk_bf16_f32 v132, v86, v87
	v_cvt_pk_bf16_f32 v133, v88, v89
	ds_write_b128 v0, v[130:133] offset:4672
	v_cvt_pk_bf16_f32 v130, v74, v75
	v_cvt_pk_bf16_f32 v131, v76, v77
	v_cvt_pk_bf16_f32 v132, v78, v79
	v_cvt_pk_bf16_f32 v133, v80, v81
	ds_write_b128 v0, v[130:133] offset:6912
	v_cvt_pk_bf16_f32 v130, v66, v67
	v_cvt_pk_bf16_f32 v131, v68, v69
	v_cvt_pk_bf16_f32 v132, v70, v71
	v_cvt_pk_bf16_f32 v133, v72, v73
	ds_write_b128 v0, v[130:133] offset:6976
	v_cvt_pk_bf16_f32 v130, v58, v59
	v_cvt_pk_bf16_f32 v131, v60, v61
	v_cvt_pk_bf16_f32 v132, v62, v63
	v_cvt_pk_bf16_f32 v133, v64, v65
	ds_write_b128 v0, v[130:133] offset:9216
	v_cvt_pk_bf16_f32 v130, v50, v51
	v_cvt_pk_bf16_f32 v131, v52, v53
	v_cvt_pk_bf16_f32 v132, v54, v55
	v_cvt_pk_bf16_f32 v133, v56, v57
	ds_write_b128 v0, v[130:133] offset:9280
	v_cvt_pk_bf16_f32 v130, v42, v43
	v_cvt_pk_bf16_f32 v131, v44, v45
	v_cvt_pk_bf16_f32 v132, v46, v47
	v_cvt_pk_bf16_f32 v133, v48, v49
	ds_write_b128 v0, v[130:133] offset:11520
	v_cvt_pk_bf16_f32 v130, v34, v35
	v_cvt_pk_bf16_f32 v131, v36, v37
	v_cvt_pk_bf16_f32 v132, v38, v39
	v_cvt_pk_bf16_f32 v133, v40, v41
	ds_write_b128 v0, v[130:133] offset:11584
	v_cvt_pk_bf16_f32 v130, v26, v27
	v_cvt_pk_bf16_f32 v131, v28, v29
	v_cvt_pk_bf16_f32 v132, v30, v31
	v_cvt_pk_bf16_f32 v133, v32, v33
	ds_write_b128 v0, v[130:133] offset:13824
	v_cvt_pk_bf16_f32 v130, v18, v19
	v_cvt_pk_bf16_f32 v131, v20, v21
	v_cvt_pk_bf16_f32 v132, v22, v23
	v_cvt_pk_bf16_f32 v133, v24, v25
	ds_write_b128 v0, v[130:133] offset:13888
	v_cvt_pk_bf16_f32 v130, v10, v11
	v_cvt_pk_bf16_f32 v131, v12, v13
	v_cvt_pk_bf16_f32 v132, v14, v15
	v_cvt_pk_bf16_f32 v133, v16, v17
	ds_write_b128 v0, v[130:133] offset:16128
	v_cvt_pk_bf16_f32 v130, v2, v3
	v_cvt_pk_bf16_f32 v131, v4, v5
	v_cvt_pk_bf16_f32 v132, v6, v7
	v_cvt_pk_bf16_f32 v133, v8, v9
	ds_write_b128 v0, v[130:133] offset:16192
	v_and_b32_e32 v0, 0xffffff80, v136
	v_add_u32_e32 v130, s48, v0
	v_ashrrev_i32_e32 v131, 31, v130
	v_lshlrev_b64 v[130:131], 11, v[130:131]
	v_lshl_add_u64 v[130:131], s[38:39], 0, v[130:131]
	v_and_b32_e32 v0, 64, v136
	v_lshl_add_u64 v[130:131], s[46:47], 1, v[130:131]
	v_lshlrev_b32_e32 v0, 1, v0
	v_lshl_add_u64 v[138:139], v[130:131], 0, v[0:1]
	v_lshlrev_b32_e32 v0, 4, v136
	v_and_b32_e32 v0, 0x70, v0
	v_bfe_u32 v140, v136, 3, 3
	v_or_b32_e32 v130, v137, v0
	s_waitcnt lgkmcnt(0)
	v_mad_u32_u24 v137, v140, s4, v130
	ds_read_b128 v[66:69], v137
	ds_read_b128 v[70:73], v137 offset:1152
	ds_read_b128 v[74:77], v137 offset:2304
	ds_read_b128 v[78:81], v137 offset:3456
	ds_read_b128 v[82:85], v137 offset:4608
	ds_read_b128 v[86:89], v137 offset:5760
	ds_read_b128 v[90:93], v137 offset:6912
	ds_read_b128 v[94:97], v137 offset:8064
	ds_read_b128 v[98:101], v137 offset:9216
	ds_read_b128 v[102:105], v137 offset:10368
	ds_read_b128 v[106:109], v137 offset:11520
	ds_read_b128 v[110:113], v137 offset:12672
	ds_read_b128 v[114:117], v137 offset:13824
	ds_read_b128 v[118:121], v137 offset:14976
	ds_read_b128 v[122:125], v137 offset:16128
	ds_read_b128 v[126:129], v137 offset:17280
	v_lshl_add_u64 v[138:139], v[138:139], 0, v[0:1]
	v_lshlrev_b32_e32 v0, 11, v140
	v_lshl_add_u64 v[140:141], v[138:139], 0, v[0:1]
	s_mov_b64 s[50:51], 0
	s_waitcnt lgkmcnt(15)
	global_store_dwordx4 v[140:141], v[66:69], off
	v_or_b32_e32 v140, 0x4000, v0
	v_mov_b32_e32 v141, v1
	v_lshl_add_u64 v[140:141], v[138:139], 0, v[140:141]
	s_waitcnt lgkmcnt(14)
	global_store_dwordx4 v[140:141], v[70:73], off
	v_or_b32_e32 v140, 0x8000, v0
	v_mov_b32_e32 v141, v1
	v_lshl_add_u64 v[140:141], v[138:139], 0, v[140:141]
	s_waitcnt lgkmcnt(13)
	global_store_dwordx4 v[140:141], v[74:77], off
	v_or_b32_e32 v140, 0xc000, v0
	v_mov_b32_e32 v141, v1
	v_lshl_add_u64 v[140:141], v[138:139], 0, v[140:141]
	s_waitcnt lgkmcnt(12)
	global_store_dwordx4 v[140:141], v[78:81], off
	v_or_b32_e32 v140, 0x10000, v0
	v_mov_b32_e32 v141, v1
	v_lshl_add_u64 v[140:141], v[138:139], 0, v[140:141]
	s_waitcnt lgkmcnt(11)
	global_store_dwordx4 v[140:141], v[82:85], off
	v_or_b32_e32 v140, 0x14000, v0
	v_mov_b32_e32 v141, v1
	v_lshl_add_u64 v[140:141], v[138:139], 0, v[140:141]
	s_waitcnt lgkmcnt(10)
	global_store_dwordx4 v[140:141], v[86:89], off
	v_or_b32_e32 v140, 0x18000, v0
	v_mov_b32_e32 v141, v1
	v_lshl_add_u64 v[140:141], v[138:139], 0, v[140:141]
	s_waitcnt lgkmcnt(9)
	global_store_dwordx4 v[140:141], v[90:93], off
	v_or_b32_e32 v140, 0x1c000, v0
	v_mov_b32_e32 v141, v1
	v_lshl_add_u64 v[140:141], v[138:139], 0, v[140:141]
	s_waitcnt lgkmcnt(8)
	global_store_dwordx4 v[140:141], v[94:97], off
	v_or_b32_e32 v140, 0x20000, v0
	v_mov_b32_e32 v141, v1
	v_lshl_add_u64 v[140:141], v[138:139], 0, v[140:141]
	s_waitcnt lgkmcnt(7)
	global_store_dwordx4 v[140:141], v[98:101], off
	v_or_b32_e32 v140, 0x24000, v0
	v_mov_b32_e32 v141, v1
	v_lshl_add_u64 v[140:141], v[138:139], 0, v[140:141]
	s_waitcnt lgkmcnt(6)
	global_store_dwordx4 v[140:141], v[102:105], off
	v_or_b32_e32 v140, 0x28000, v0
	v_mov_b32_e32 v141, v1
	v_lshl_add_u64 v[140:141], v[138:139], 0, v[140:141]
	s_waitcnt lgkmcnt(5)
	global_store_dwordx4 v[140:141], v[106:109], off
	v_or_b32_e32 v140, 0x2c000, v0
	v_mov_b32_e32 v141, v1
	v_lshl_add_u64 v[140:141], v[138:139], 0, v[140:141]
	s_waitcnt lgkmcnt(4)
	global_store_dwordx4 v[140:141], v[110:113], off
	v_or_b32_e32 v140, 0x30000, v0
	v_mov_b32_e32 v141, v1
	v_lshl_add_u64 v[140:141], v[138:139], 0, v[140:141]
	s_waitcnt lgkmcnt(3)
	global_store_dwordx4 v[140:141], v[114:117], off
	v_or_b32_e32 v140, 0x34000, v0
	v_mov_b32_e32 v141, v1
	v_lshl_add_u64 v[140:141], v[138:139], 0, v[140:141]
	s_waitcnt lgkmcnt(2)
	global_store_dwordx4 v[140:141], v[118:121], off
	v_or_b32_e32 v140, 0x38000, v0
	v_mov_b32_e32 v141, v1
	v_lshl_add_u64 v[140:141], v[138:139], 0, v[140:141]
	v_or_b32_e32 v0, 0x3c000, v0
	s_waitcnt lgkmcnt(1)
	global_store_dwordx4 v[140:141], v[122:125], off
	v_lshl_add_u64 v[138:139], v[138:139], 0, v[0:1]
	s_waitcnt lgkmcnt(0)
	global_store_dwordx4 v[138:139], v[126:129], off
	s_waitcnt lgkmcnt(0)
	s_barrier
